# grid-barrier polling loops poll back-to-back (s_sleep 1 removed from all 27 poll sites)
# speedup vs baseline: 1.0036x; 1.0036x over previous
.LBB0_97:
	flat_load_dword v25, v[0:1] offset:1024 sc1
	flat_load_dword v10, v[0:1] offset:1280 sc1
	flat_load_dword v11, v[0:1] offset:1536 sc1
	flat_load_dword v12, v[0:1] offset:1792 sc1
	flat_load_dword v13, v[0:1] offset:2048 sc1
	flat_load_dword v14, v[0:1] offset:2304 sc1
	flat_load_dword v15, v[0:1] offset:2560 sc1
	flat_load_dword v16, v[0:1] offset:2816 sc1
	flat_load_dword v17, v[0:1] offset:3072 sc1
	flat_load_dword v18, v[0:1] offset:3328 sc1
	flat_load_dword v19, v[0:1] offset:3584 sc1
	flat_load_dword v20, v[0:1] offset:3840 sc1
	flat_load_dword v21, v[2:3] sc1
	flat_load_dword v22, v[4:5] sc1
	flat_load_dword v23, v[6:7] sc1
	flat_load_dword v24, v[8:9] sc1
	s_or_b64 s[8:9], s[8:9], exec
	s_or_b64 s[6:7], s[6:7], exec
	s_waitcnt vmcnt(0) lgkmcnt(0)
	v_add_u32_e32 v26, v10, v25
	v_add_u32_e32 v26, v26, v11
	v_add_u32_e32 v26, v26, v12
	v_add_u32_e32 v26, v26, v13
	v_add_u32_e32 v26, v26, v14
	v_add_u32_e32 v26, v26, v15
	v_add_u32_e32 v26, v26, v16
	v_add_u32_e32 v26, v26, v17
	v_add_u32_e32 v26, v26, v18
	v_add_u32_e32 v26, v26, v19
	v_add_u32_e32 v26, v26, v20
	v_add_u32_e32 v26, v26, v21
	v_add_u32_e32 v26, v26, v22
	v_add_u32_e32 v26, v26, v23
	v_add_u32_e32 v26, v26, v24
	v_cmp_ne_u32_e32 vcc, s20, v26
	s_and_saveexec_b64 s[10:11], vcc
	s_cbranch_execz .LBB0_96
	s_and_b32 s14, s21, 0xff
	s_mov_b64 s[12:13], -1
	s_cmp_eq_u32 s14, 0
	s_mov_b64 s[16:17], -1
	s_mov_b64 s[14:15], -1
	s_nop 0
	s_cbranch_scc1 .LBB0_100
	s_and_saveexec_b64 s[18:19], s[16:17]
	s_cbranch_execz .LBB0_95
	s_branch .LBB0_103

.LBB0_111:
	s_and_b32 s16, s23, 0xff
	s_mov_b64 s[14:15], -1
	s_cmp_lg_u32 s16, 0
	s_mov_b64 s[16:17], -1
	s_nop 0
	s_cbranch_scc1 .LBB0_115
	v_mov_b64_e32 v[2:3], s[36:37]
	flat_load_dword v0, v[2:3] offset:512 sc1
	s_mov_b64 s[16:17], 0
	s_mov_b64 s[18:19], -1
	s_waitcnt vmcnt(0) lgkmcnt(0)
	v_cmp_eq_u32_e32 vcc, 0, v0
	s_and_saveexec_b64 s[20:21], vcc
	s_cmp_lt_u32 s23, 0x400001
	s_cselect_b64 s[16:17], -1, 0
	s_xor_b64 s[18:19], exec, -1
	s_and_b64 s[16:17], s[16:17], exec
	s_or_b64 exec, exec, s[20:21]

.LBB0_125:
	s_and_b32 s16, s22, 0xff
	s_mov_b64 s[14:15], -1
	s_cmp_lg_u32 s16, 0
	s_mov_b64 s[16:17], -1
	s_nop 0
	s_cbranch_scc1 .LBB0_129
	v_mov_b64_e32 v[2:3], s[36:37]
	flat_load_dword v0, v[2:3] offset:512 sc1
	s_mov_b64 s[16:17], 0
	s_mov_b64 s[18:19], -1
	s_waitcnt vmcnt(0) lgkmcnt(0)
	v_cmp_eq_u32_e32 vcc, 0, v0
	s_and_saveexec_b64 s[20:21], vcc
	s_cmp_lt_u32 s22, 0x400001
	s_cselect_b64 s[16:17], -1, 0
	s_xor_b64 s[18:19], exec, -1
	s_and_b64 s[16:17], s[16:17], exec
	s_or_b64 exec, exec, s[20:21]

.LBB0_162:
	s_and_b32 s18, s17, 0xff
	s_mov_b64 s[20:21], -1
	s_cmp_lg_u32 s18, 0
	s_mov_b64 s[22:23], -1
	s_nop 0
	s_cbranch_scc1 .LBB0_166
	v_mov_b64_e32 v[2:3], s[2:3]
	flat_load_dword v2, v[2:3] offset:512 sc1
	s_mov_b64 s[22:23], 0
	s_mov_b64 s[24:25], -1
	s_waitcnt vmcnt(0) lgkmcnt(0)
	v_cmp_eq_u32_e32 vcc, 0, v2
	s_and_saveexec_b64 s[26:27], vcc
	s_cmp_lt_u32 s17, 0x400001
	s_cselect_b64 s[18:19], -1, 0
	s_xor_b64 s[24:25], exec, -1
	s_and_b64 s[22:23], s[18:19], exec
	s_or_b64 exec, exec, s[26:27]

.LBB0_176:
	s_and_b32 s17, s16, 0xff
	s_mov_b64 s[20:21], -1
	s_cmp_lg_u32 s17, 0
	s_mov_b64 s[22:23], -1
	s_nop 0
	s_cbranch_scc1 .LBB0_180
	v_mov_b64_e32 v[2:3], s[2:3]
	flat_load_dword v2, v[2:3] offset:512 sc1
	s_mov_b64 s[22:23], 0
	s_mov_b64 s[24:25], -1
	s_waitcnt vmcnt(0) lgkmcnt(0)
	v_cmp_eq_u32_e32 vcc, 0, v2
	s_and_saveexec_b64 s[26:27], vcc
	s_cmp_lt_u32 s16, 0x400001
	s_cselect_b64 s[18:19], -1, 0
	s_xor_b64 s[24:25], exec, -1
	s_and_b64 s[22:23], s[18:19], exec
	s_or_b64 exec, exec, s[26:27]

.LBB0_231:
	s_and_b32 s18, s17, 0xff
	s_mov_b64 s[22:23], -1
	s_cmp_lg_u32 s18, 0
	s_mov_b64 s[24:25], -1
	s_nop 0
	s_cbranch_scc1 .LBB0_235
	v_mov_b64_e32 v[2:3], s[4:5]
	flat_load_dword v2, v[2:3] offset:512 sc1
	s_mov_b64 s[24:25], 0
	s_mov_b64 s[26:27], -1
	s_waitcnt vmcnt(0) lgkmcnt(0)
	v_cmp_eq_u32_e32 vcc, 0, v2
	s_and_saveexec_b64 s[30:31], vcc
	s_cmp_lt_u32 s17, 0x400001
	s_cselect_b64 s[18:19], -1, 0
	s_xor_b64 s[26:27], exec, -1
	s_and_b64 s[24:25], s[18:19], exec
	s_or_b64 exec, exec, s[30:31]

.LBB0_245:
	s_and_b32 s17, s16, 0xff
	s_mov_b64 s[22:23], -1
	s_cmp_lg_u32 s17, 0
	s_mov_b64 s[24:25], -1
	s_nop 0
	s_cbranch_scc1 .LBB0_249
	v_mov_b64_e32 v[2:3], s[4:5]
	flat_load_dword v2, v[2:3] offset:512 sc1
	s_mov_b64 s[24:25], 0
	s_mov_b64 s[26:27], -1
	s_waitcnt vmcnt(0) lgkmcnt(0)
	v_cmp_eq_u32_e32 vcc, 0, v2
	s_and_saveexec_b64 s[30:31], vcc
	s_cmp_lt_u32 s16, 0x400001
	s_cselect_b64 s[18:19], -1, 0
	s_xor_b64 s[26:27], exec, -1
	s_and_b64 s[24:25], s[18:19], exec
	s_or_b64 exec, exec, s[30:31]

.LBB0_1043:
	s_and_b32 s20, s19, 0xff
	s_mov_b64 s[16:17], -1
	s_cmp_lg_u32 s20, 0
	s_mov_b64 s[20:21], -1
	s_nop 0
	s_cbranch_scc1 .LBB0_1047
	v_mov_b64_e32 v[2:3], s[2:3]
	flat_load_dword v2, v[2:3] offset:512 sc1
	s_mov_b64 s[20:21], 0
	s_mov_b64 s[22:23], -1
	s_waitcnt vmcnt(0) lgkmcnt(0)
	v_cmp_eq_u32_e32 vcc, 0, v2
	s_and_saveexec_b64 s[24:25], vcc
	s_cmp_lt_u32 s19, 0x400001
	s_cselect_b64 s[20:21], -1, 0
	s_xor_b64 s[22:23], exec, -1
	s_and_b64 s[20:21], s[20:21], exec
	s_or_b64 exec, exec, s[24:25]

.LBB0_1057:
	s_and_b32 s19, s18, 0xff
	s_mov_b64 s[16:17], -1
	s_cmp_lg_u32 s19, 0
	s_mov_b64 s[20:21], -1
	s_nop 0
	s_cbranch_scc1 .LBB0_1061
	v_mov_b64_e32 v[2:3], s[2:3]
	flat_load_dword v2, v[2:3] offset:512 sc1
	s_mov_b64 s[20:21], 0
	s_mov_b64 s[22:23], -1
	s_waitcnt vmcnt(0) lgkmcnt(0)
	v_cmp_eq_u32_e32 vcc, 0, v2
	s_and_saveexec_b64 s[24:25], vcc
	s_cmp_lt_u32 s18, 0x400001
	s_cselect_b64 s[20:21], -1, 0
	s_xor_b64 s[22:23], exec, -1
	s_and_b64 s[20:21], s[20:21], exec
	s_or_b64 exec, exec, s[24:25]

.LBB0_1108:
	s_and_b32 s24, s19, 0xff
	s_mov_b64 s[22:23], -1
	s_cmp_lg_u32 s24, 0
	s_mov_b64 s[24:25], -1
	s_nop 0
	s_cbranch_scc1 .LBB0_1112
	v_mov_b64_e32 v[2:3], s[6:7]
	flat_load_dword v2, v[2:3] offset:512 sc1
	s_mov_b64 s[24:25], 0
	s_mov_b64 s[26:27], -1
	s_waitcnt vmcnt(0) lgkmcnt(0)
	v_cmp_eq_u32_e32 vcc, 0, v2
	s_and_saveexec_b64 s[30:31], vcc
	s_cmp_lt_u32 s19, 0x400001
	s_cselect_b64 s[24:25], -1, 0
	s_xor_b64 s[26:27], exec, -1
	s_and_b64 s[24:25], s[24:25], exec
	s_or_b64 exec, exec, s[30:31]

.LBB0_1122:
	s_and_b32 s19, s18, 0xff
	s_mov_b64 s[22:23], -1
	s_cmp_lg_u32 s19, 0
	s_mov_b64 s[24:25], -1
	s_nop 0
	s_cbranch_scc1 .LBB0_1126
	v_mov_b64_e32 v[2:3], s[6:7]
	flat_load_dword v2, v[2:3] offset:512 sc1
	s_mov_b64 s[24:25], 0
	s_mov_b64 s[26:27], -1
	s_waitcnt vmcnt(0) lgkmcnt(0)
	v_cmp_eq_u32_e32 vcc, 0, v2
	s_and_saveexec_b64 s[30:31], vcc
	s_cmp_lt_u32 s18, 0x400001
	s_cselect_b64 s[24:25], -1, 0
	s_xor_b64 s[26:27], exec, -1
	s_and_b64 s[24:25], s[24:25], exec
	s_or_b64 exec, exec, s[30:31]
